# v26 plus s_nop spacing after v_readlane at the start of the hand-written P2c/P2d blocks (formal VALU-SGPR-write to VALU-read distance)
# baseline (speedup 1.0000x reference)
; __global__ void __launch_bounds__(NTHR, 2) hybrid_block_fwd(Args a) {
;     ...
;         const int c2 = gtid & 1023, chunk = (gtid >> 10) & (NCH - 1), b = gtid >> 16;
;         const size_t r0 = (size_t)b * SEQ + (size_t)chunk * CH_L;
;         const u32x2* pab = (const u32x2*)((const unsigned*)AF + r0 * LW) + c2;
;         f32x2 P = (f32x2){1.f, 1.f}, H = (f32x2){0.f, 0.f};
; #pragma unroll 32
;         for (int i = 0; i < CH_L; ++i) { const u32x2 q = pab[(size_t)i * (LW / 2)];
.LBB0_613:
	s_or_b64 exec, exec, s[0:1]
	s_waitcnt lgkmcnt(0)
	v_mov_b32_e32 v0, v212
	v_readlane_b32 s0, v248, 8
	s_barrier
	s_nop 1
	v_add_u32_e32 v1, s0, v0
	v_and_b32_e32 v1, 0x3ff, v1
	v_lshlrev_b32_e32 v2, 3, v1
	v_add_u32_e32 v6, 0x100000, v2
	s_lshr_b32 s9, s0, 10
	s_lshl_b32 s10, s9, 20
	s_add_u32 s12, s92, s10
	s_addc_u32 s13, s93, 0
	global_load_dwordx2 v[32:33], v2, s[12:13]
	s_add_u32 s12, s12, 0x2000
	s_addc_u32 s13, s13, 0
	global_load_dwordx2 v[34:35], v2, s[12:13]
	s_add_u32 s12, s12, 0x2000
	s_addc_u32 s13, s13, 0
	global_load_dwordx2 v[36:37], v2, s[12:13]
	s_add_u32 s12, s12, 0x2000
	s_addc_u32 s13, s13, 0
	global_load_dwordx2 v[38:39], v2, s[12:13]
	s_add_u32 s12, s12, 0x2000
	s_addc_u32 s13, s13, 0
	global_load_dwordx2 v[40:41], v2, s[12:13]
	s_add_u32 s12, s12, 0x2000
	s_addc_u32 s13, s13, 0
	global_load_dwordx2 v[42:43], v2, s[12:13]
	s_add_u32 s12, s12, 0x2000
	s_addc_u32 s13, s13, 0
	global_load_dwordx2 v[44:45], v2, s[12:13]
	s_add_u32 s12, s12, 0x2000
	s_addc_u32 s13, s13, 0
	global_load_dwordx2 v[46:47], v2, s[12:13]
	s_add_u32 s12, s12, 0x2000
	s_addc_u32 s13, s13, 0
	global_load_dwordx2 v[48:49], v2, s[12:13]
	s_add_u32 s12, s12, 0x2000
	s_addc_u32 s13, s13, 0
	global_load_dwordx2 v[50:51], v2, s[12:13]
	s_add_u32 s12, s12, 0x2000
	s_addc_u32 s13, s13, 0
	global_load_dwordx2 v[52:53], v2, s[12:13]
	s_add_u32 s12, s12, 0x2000
	s_addc_u32 s13, s13, 0
	global_load_dwordx2 v[54:55], v2, s[12:13]
	s_add_u32 s12, s12, 0x2000
	s_addc_u32 s13, s13, 0
	global_load_dwordx2 v[56:57], v2, s[12:13]
	s_add_u32 s12, s12, 0x2000
	s_addc_u32 s13, s13, 0
	global_load_dwordx2 v[58:59], v2, s[12:13]
	s_add_u32 s12, s12, 0x2000
	s_addc_u32 s13, s13, 0
	global_load_dwordx2 v[60:61], v2, s[12:13]
	s_add_u32 s12, s12, 0x2000
	s_addc_u32 s13, s13, 0
	global_load_dwordx2 v[62:63], v2, s[12:13]
	s_add_u32 s12, s12, 0x2000
	s_addc_u32 s13, s13, 0
	global_load_dwordx2 v[64:65], v2, s[12:13]
	s_add_u32 s12, s12, 0x2000
	s_addc_u32 s13, s13, 0
	global_load_dwordx2 v[66:67], v2, s[12:13]
	s_add_u32 s12, s12, 0x2000
	s_addc_u32 s13, s13, 0
	global_load_dwordx2 v[68:69], v2, s[12:13]
	s_add_u32 s12, s12, 0x2000
	s_addc_u32 s13, s13, 0
	global_load_dwordx2 v[70:71], v2, s[12:13]
	s_add_u32 s12, s12, 0x2000
	s_addc_u32 s13, s13, 0
	global_load_dwordx2 v[72:73], v2, s[12:13]
	s_add_u32 s12, s12, 0x2000
	s_addc_u32 s13, s13, 0
	global_load_dwordx2 v[74:75], v2, s[12:13]
	s_add_u32 s12, s12, 0x2000
	s_addc_u32 s13, s13, 0
	global_load_dwordx2 v[76:77], v2, s[12:13]
	s_add_u32 s12, s12, 0x2000
	s_addc_u32 s13, s13, 0
	global_load_dwordx2 v[78:79], v2, s[12:13]
	s_add_u32 s12, s12, 0x2000
	s_addc_u32 s13, s13, 0
	global_load_dwordx2 v[80:81], v2, s[12:13]
	s_add_u32 s12, s12, 0x2000
	s_addc_u32 s13, s13, 0
	global_load_dwordx2 v[82:83], v2, s[12:13]
	s_add_u32 s12, s12, 0x2000
	s_addc_u32 s13, s13, 0
	global_load_dwordx2 v[84:85], v2, s[12:13]
	s_add_u32 s12, s12, 0x2000
	s_addc_u32 s13, s13, 0
	global_load_dwordx2 v[86:87], v2, s[12:13]
	s_add_u32 s12, s12, 0x2000
	s_addc_u32 s13, s13, 0
	global_load_dwordx2 v[88:89], v2, s[12:13]
	s_add_u32 s12, s12, 0x2000
	s_addc_u32 s13, s13, 0
	global_load_dwordx2 v[90:91], v2, s[12:13]
	s_add_u32 s12, s12, 0x2000
	s_addc_u32 s13, s13, 0
	global_load_dwordx2 v[92:93], v2, s[12:13]
	s_add_u32 s12, s12, 0x2000
	s_addc_u32 s13, s13, 0
	global_load_dwordx2 v[94:95], v2, s[12:13]
	s_add_u32 s12, s12, 0x2000
	s_addc_u32 s13, s13, 0
	v_mov_b32_e32 v8, 1.0
	v_mov_b32_e32 v9, 1.0
	v_mov_b32_e32 v10, 0
	v_mov_b32_e32 v11, 0
	s_mov_b32 s8, 3

; __device__ __forceinline__ float bf_lo(unsigned w) { return __uint_as_float(w << 16); }
; __device__ __forceinline__ float bf_hi(unsigned w) { return __uint_as_float(w & 0xffff0000u); }
; __global__ void __launch_bounds__(NTHR, 2) hybrid_block_fwd(Args a) {
;     ...
;         const int c2 = gtid & 1023, chunk = (gtid >> 10) & (NCH - 1), b = gtid >> 16;
;         f32x2 H = (f32x2){0.f, 0.f};
; #pragma unroll 4
;         for (int j = 0; j < chunk; ++j) { const f32x2 P = ((const f32x2*)(AGGP + (size_t)(b * NCH + j) * LW))[c2], Hj = ((const f32x2*)(AGGH + (size_t)(b * NCH + j) * LW))[c2]; H = P * H + Hj; }
;         const size_t r0 = (size_t)b * SEQ + (size_t)chunk * CH_L;
;         const u32x2* pab = (const u32x2*)((const unsigned*)AF + r0 * LW) + c2;
;         const unsigned* pg = (const unsigned*)(GELU_U + r0 * LW) + c2; unsigned* po = (unsigned*)(YCAT + r0 * KC + PW) + c2;
; #pragma unroll 16
;         for (int i = 0; i < CH_L; ++i) {
;             const u32x2 q = pab[(size_t)i * (LW / 2)]; const f32x2 av = (f32x2){__builtin_amdgcn_exp2f(bf_lo(q.x)), __builtin_amdgcn_exp2f(bf_lo(q.y))}, bv = (f32x2){bf_hi(q.x), bf_hi(q.y)}; const unsigned gq = pg[(size_t)i * (LW / 2)];
.LBB0_669:
	s_or_b64 exec, exec, s[8:9]
	s_waitcnt lgkmcnt(0)
	v_mov_b32_e32 v0, v212
	v_readlane_b32 s8, v248, 8
	s_barrier
	s_nop 1
	v_add_u32_e32 v1, s8, v0
	v_and_b32_e32 v1, 0x3ff, v1
	v_lshlrev_b32_e32 v2, 3, v1
	v_lshlrev_b32_e32 v3, 2, v1
	v_add_u32_e32 v6, 0x100000, v2
	s_lshr_b32 s9, s8, 10
	s_and_b32 s10, s9, 63
	s_lshr_b32 s11, s9, 6
	s_lshl_b32 s21, s9, 20
	s_add_u32 s12, s92, s21
	s_addc_u32 s13, s93, 0
	s_lshl_b32 s21, s9, 19
	s_add_u32 s14, s94, s21
	s_addc_u32 s15, s95, 0
	s_add_u32 s14, s14, 0x9f00000
	s_addc_u32 s15, s15, 0
	s_mul_i32 s21, s9, 0xc0000
	s_add_u32 s18, s94, s21
	s_addc_u32 s19, s95, 0
	s_add_u32 s18, s18, 0x15f00800
	s_addc_u32 s19, s19, 0
	s_lshl_b32 s21, s11, 19
	s_add_u32 s0, s94, s21
	s_addc_u32 s1, s95, 0
	s_add_u32 s0, s0, 0x100000
	s_addc_u32 s1, s1, 0
	global_load_dwordx2 v[32:33], v2, s[12:13] nt
	global_load_dword v64, v3, s[14:15] nt
	s_add_u32 s12, s12, 0x2000
	s_addc_u32 s13, s13, 0
	s_add_u32 s14, s14, 0x1000
	s_addc_u32 s15, s15, 0
	global_load_dwordx2 v[34:35], v2, s[12:13] nt
	global_load_dword v65, v3, s[14:15] nt
	s_add_u32 s12, s12, 0x2000
	s_addc_u32 s13, s13, 0
	s_add_u32 s14, s14, 0x1000
	s_addc_u32 s15, s15, 0
	global_load_dwordx2 v[36:37], v2, s[12:13] nt
	global_load_dword v66, v3, s[14:15] nt
	s_add_u32 s12, s12, 0x2000
	s_addc_u32 s13, s13, 0
	s_add_u32 s14, s14, 0x1000
	s_addc_u32 s15, s15, 0
	global_load_dwordx2 v[38:39], v2, s[12:13] nt
	global_load_dword v67, v3, s[14:15] nt
	s_add_u32 s12, s12, 0x2000
	s_addc_u32 s13, s13, 0
	s_add_u32 s14, s14, 0x1000
	s_addc_u32 s15, s15, 0
	global_load_dwordx2 v[40:41], v2, s[12:13] nt
	global_load_dword v68, v3, s[14:15] nt
	s_add_u32 s12, s12, 0x2000
	s_addc_u32 s13, s13, 0
	s_add_u32 s14, s14, 0x1000
	s_addc_u32 s15, s15, 0
	global_load_dwordx2 v[42:43], v2, s[12:13] nt
	global_load_dword v69, v3, s[14:15] nt
	s_add_u32 s12, s12, 0x2000
	s_addc_u32 s13, s13, 0
	s_add_u32 s14, s14, 0x1000
	s_addc_u32 s15, s15, 0
	global_load_dwordx2 v[44:45], v2, s[12:13] nt
	global_load_dword v70, v3, s[14:15] nt
	s_add_u32 s12, s12, 0x2000
	s_addc_u32 s13, s13, 0
	s_add_u32 s14, s14, 0x1000
	s_addc_u32 s15, s15, 0
	global_load_dwordx2 v[46:47], v2, s[12:13] nt
	global_load_dword v71, v3, s[14:15] nt
	s_add_u32 s12, s12, 0x2000
	s_addc_u32 s13, s13, 0
	s_add_u32 s14, s14, 0x1000
	s_addc_u32 s15, s15, 0
	global_load_dwordx2 v[48:49], v2, s[12:13] nt
	global_load_dword v72, v3, s[14:15] nt
	s_add_u32 s12, s12, 0x2000
	s_addc_u32 s13, s13, 0
	s_add_u32 s14, s14, 0x1000
	s_addc_u32 s15, s15, 0
	global_load_dwordx2 v[50:51], v2, s[12:13] nt
	global_load_dword v73, v3, s[14:15] nt
	s_add_u32 s12, s12, 0x2000
	s_addc_u32 s13, s13, 0
	s_add_u32 s14, s14, 0x1000
	s_addc_u32 s15, s15, 0
	global_load_dwordx2 v[52:53], v2, s[12:13] nt
	global_load_dword v74, v3, s[14:15] nt
	s_add_u32 s12, s12, 0x2000
	s_addc_u32 s13, s13, 0
	s_add_u32 s14, s14, 0x1000
	s_addc_u32 s15, s15, 0
	global_load_dwordx2 v[54:55], v2, s[12:13] nt
	global_load_dword v75, v3, s[14:15] nt
	s_add_u32 s12, s12, 0x2000
	s_addc_u32 s13, s13, 0
	s_add_u32 s14, s14, 0x1000
	s_addc_u32 s15, s15, 0
	global_load_dwordx2 v[56:57], v2, s[12:13] nt
	global_load_dword v76, v3, s[14:15] nt
	s_add_u32 s12, s12, 0x2000
	s_addc_u32 s13, s13, 0
	s_add_u32 s14, s14, 0x1000
	s_addc_u32 s15, s15, 0
	global_load_dwordx2 v[58:59], v2, s[12:13] nt
	global_load_dword v77, v3, s[14:15] nt
	s_add_u32 s12, s12, 0x2000
	s_addc_u32 s13, s13, 0
	s_add_u32 s14, s14, 0x1000
	s_addc_u32 s15, s15, 0
	global_load_dwordx2 v[60:61], v2, s[12:13] nt
	global_load_dword v78, v3, s[14:15] nt
	s_add_u32 s12, s12, 0x2000
	s_addc_u32 s13, s13, 0
	s_add_u32 s14, s14, 0x1000
	s_addc_u32 s15, s15, 0
	global_load_dwordx2 v[62:63], v2, s[12:13] nt
	global_load_dword v79, v3, s[14:15] nt
	s_add_u32 s12, s12, 0x2000
	s_addc_u32 s13, s13, 0
	s_add_u32 s14, s14, 0x1000
	s_addc_u32 s15, s15, 0
	v_mov_b32_e32 v4, 0
	v_mov_b32_e32 v5, 0
	s_cmp_eq_u32 s10, 0
	s_cbranch_scc1 .Lp2d_prefix_done
